# QKV GEMM epilogue stores the fp8 V copy head-major as well; the re-layout pass is gone
# speedup vs baseline: 1.0031x; 1.0003x over previous
; #define LAS __attribute__((address_space(3)))
; __device__ __forceinline__ void sparse_unit7(const bf16_t* QKV, const unsigned char* K8, const unsigned char* V8, const int (&selv)[4], bf16_t* OB, LAS unsigned char* wl, int t, int h, int lane) {
;     LAS int* wsel = (LAS int*)wl; LAS unsigned* otw = (LAS unsigned*)(wl + 1024); LAS float* ptw = (LAS float*)(wl + 2048);
;     const int n16 = lane & 15, slab = lane >> 4, half = lane >> 5, l4 = (lane & 31) * 4;
;     const bf16_t* qrow = QKV + (size_t)t * QKVW + COL_BQ + h * 128 + 16 * slab;
;     long qa[4];
; #pragma unroll
;     for (int ks = 0; ks < 4; ++ks) { const u32x4 raw = *(const u32x4*)(qrow + 8 * (ks & 1) + 64 * (ks >> 1)); const unsigned w[4] = {raw.x, raw.y, raw.z, raw.w}; float x[8];
; #pragma unroll
;         for (int i = 0; i < 4; ++i) { x[2 * i] = bf2f(w[i] & 0xffffu); x[2 * i + 1] = __builtin_bit_cast(float, w[i] & 0xffff0000u); }
;         const u32x2 f = to_fp8x8(x); qa[ks] = (long)(((unsigned long long)f.y << 32) | f.x); }
;     const unsigned char* K8h = K8 + h * 128; const unsigned char* V8h = V8 + h * 128;
; __global__ void __launch_bounds__(NTHREADS, 2) mega(Args a) {
;     ...
;                 const int h = blockIdx.x & 7, qg = (blockIdx.x >> 3) * NWAVES + wave, nqg = ((G + 7) >> 3) * NWAVES;
;                 for (int u = gw; u < SEQ * 4; u += NGW) dilated_merge(OG, LSE, OA, u >> 2, u & 3, lane);
;                 for (int rep = 0; rep < REP_SP; ++rep)
;                 if ((G & 7) == 0) { int seln[4];
; #pragma unroll
;                     for (int s = 0; s < 4; ++s) seln[s] = (int)SEL[(size_t)min(qg, SEQ - 1) * 256 + 64 * s + lane];
;                     for (int t = qg; t < SEQ; t += nqg) { int selc[4];
; #pragma unroll
;                         for (int s = 0; s < 4; ++s) selc[s] = seln[s];
;                         const int tn = min(t + nqg, SEQ - 1);
; #pragma unroll
;                         for (int s = 0; s < 4; ++s) seln[s] = (int)SEL[(size_t)tn * 256 + 64 * s + lane];
;                         sparse_unit7(QKV, K8, V8, selc, OB, lds + wave * 4096, t, h, lane); } }
.LBB0_160:
.LBB0_161:
	v_readlane_b32 s0, v251, 0
	v_readlane_b32 s1, v250, 18
	s_nop 3
	s_and_b32 s4, s0, 7
	s_and_b32 s5, s0, -8
	s_add_i32 s34, s5, s1
	s_add_i32 s48, s94, 7
	s_and_b32 s48, s48, -8
	s_add_u32 s38, s90, 0x28600000
	s_addc_u32 s39, s91, 0
	s_lshl_b32 s5, s4, 8
	s_add_u32 s5, s5, 0x12302400
	s_add_u32 s40, s90, s5
	s_addc_u32 s41, s91, 0
	s_lshl_b32 s5, s4, 21
	s_add_u32 s0, s5, 0x3cf00000
	s_add_u32 s42, s90, s0
	s_addc_u32 s43, s91, 0
	s_add_u32 s0, s5, 0x3af00000
	s_add_u32 s44, s90, s0
	s_addc_u32 s45, s91, 0
	s_lshl_b32 s5, s4, 8
	s_add_u32 s0, s5, 0x29e00000
	s_add_u32 s46, s90, s0
	s_addc_u32 s47, s91, 0
	s_lshl_b32 s0, s1, 13
	v_and_b32_e32 v218, 15, v182
	v_lshrrev_b32_e32 v219, 4, v182
	v_and_b32_e32 v246, 7, v182
	v_lshrrev_b32_e32 v247, 3, v182
	v_lshlrev_b32_e32 v200, 6, v247
	v_lshlrev_b32_e32 v201, 5, v219
	v_xor_b32_e32 v248, v246, v247
	v_lshlrev_b32_e32 v202, 4, v248
	v_lshlrev_b32_e32 v203, 4, v246
	v_lshl_add_u32 v224, v182, 4, s0
	v_and_b32_e32 v248, 7, v218
	v_lshrrev_b32_e32 v249, 3, v218
	v_lshlrev_b32_e32 v227, 4, v249
	v_lshlrev_b32_e32 v225, 10, v249
	v_lshl_add_u32 v225, v248, 7, v225
	v_add_u32_e32 v225, s0, v225
	v_xor_b32_e32 v217, v219, v248
	v_xor_b32_e32 v226, 4, v217
	v_lshl_add_u32 v226, v226, 4, v225
	v_lshl_add_u32 v225, v217, 4, v225
	v_lshlrev_b32_e32 v217, 5, v248
	v_lshl_add_u32 v217, v219, 3, v217
	v_sub_u32_e32 v216, v217, v161
	v_lshlrev_b32_e32 v216, 1, v216
	v_add_u32_e32 v217, v217, v249
	v_lshlrev_b32_e32 v248, 4, v218
	v_lshl_add_u32 v248, v219, 2, v248
	v_lshrrev_b32_e32 v249, 1, v218
	v_lshl_add_u32 v248, v249, 2, v248
	v_lshlrev_b32_e32 v213, 2, v248
	s_add_i32 s1, s0, 0x1000
	v_add_u32_e32 v213, s1, v213
	v_mul_u32_u24_e32 v214, 0x90, v247
	v_add_u32_e32 v214, s1, v214
	v_lshlrev_b32_e32 v215, 5, v246
	v_lshl_add_u32 v215, v219, 3, v215
	v_cmp_eq_u32_e64 s[8:9], 0, v219
	v_cmp_eq_u32_e64 s[10:11], 1, v219
	v_cmp_eq_u32_e64 s[16:17], 2, v219
	v_cmp_eq_u32_e64 s[22:23], 3, v219
	s_lshl_b32 s0, s34, 9
	s_add_u32 s0, s38, s0
	s_addc_u32 s1, s39, 0
	s_mul_i32 s4, s34, 0x3c00
	s_add_u32 s4, s40, s4
	s_addc_u32 s5, s41, 0
	global_load_dwordx4 v[96:99], v200, s[0:1]
	global_load_dwordx4 v[100:103], v200, s[0:1] offset:16
	global_load_dwordx4 v[104:107], v200, s[0:1] offset:32
	global_load_dwordx4 v[108:111], v200, s[0:1] offset:48
	global_load_dwordx4 v[220:223], v216, s[0:1]
	global_load_dwordx4 v[230:233], v201, s[4:5]
	global_load_dwordx4 v[234:237], v201, s[4:5] offset:16
	global_load_dwordx4 v[238:241], v201, s[4:5] offset:128
	global_load_dwordx4 v[242:245], v201, s[4:5] offset:144
	s_waitcnt vmcnt(0)
	s_nop 0

; __device__ __forceinline__ unsigned pk2(float lo, float hi) { return f2bf(lo) | (f2bf(hi) << 16); }
;     __device__ __forceinline__ void operator()(const f32x4 (&acc)[2][2][4][2], const pg8::Unit& u, int wr, int wc, int fr, int fq) const {
;     ...
;                     if constexpr (MODE == 0 || MODE == 1) { v0 = v0 * scale; v1 = v1 * scale; }
;                     if constexpr (MODE == 6) { float* p = of + row * IDXW + col; *(f32x4*)p = v0; *(f32x4*)(p + 4) = v1; }
;                     else if constexpr (MODE == 0) {
;                         if (u.pn >= COL_BV / 256) {
;                             const float x8[8] = {v0[0], v0[1], v0[2], v0[3], v1[0], v1[1], v1[2], v1[3]};
;                             *(u32x2*)((unsigned char*)aux + row * 1024 + (col - COL_BV)) = to_fp8x8(x8);
;                         } else { u32x4 w; w.x = pk2(v0[0], v0[1]); w.y = pk2(v0[2], v0[3]); w.z = pk2(v1[0], v1[1]); w.w = pk2(v1[2], v1[3]);
;                             *(u32x4*)(ob + row * QKVW + col) = w; }
.LBB0_1025:
	s_add_u32 s98, s90, 0x3af00000
	s_addc_u32 s99, s91, 0
	s_add_u32 s100, s90, 0x3bf00000
	s_movk_i32 s101, 0x7f
	v_lshl_add_u32 v2, s35, 8, v214
	s_movk_i32 s11, 0x3c00
	s_cmp_lt_i32 s34, 26
	v_lshl_or_b32 v160, s34, 8, v216
	v_mad_i64_i32 v[0:1], s[40:41], v2, s11, 0
	s_cselect_b64 s[44:45], -1, 0
	v_pk_mul_f32 v[8:9], v[158:159], s[18:19] op_sel_hi:[1,0]
	v_pk_mul_f32 v[12:13], v[156:157], s[18:19] op_sel_hi:[1,0]
	v_pk_mul_f32 v[10:11], v[154:155], s[18:19] op_sel_hi:[1,0]
	v_pk_mul_f32 v[14:15], v[152:153], s[18:19] op_sel_hi:[1,0]
	s_mov_b64 s[40:41], -1
	s_and_b64 vcc, exec, s[44:45]
	v_lshl_add_u64 v[4:5], s[20:21], 0, v[0:1]
	v_ashrrev_i32_e32 v1, 31, v160
	s_nop 15
	s_nop 15
	s_cbranch_vccz .LBB0_1027
	v_cvt_pk_bf16_f32 v16, v12, v13
	v_cvt_pk_bf16_f32 v17, v8, v9
	v_cvt_pk_bf16_f32 v18, v14, v15
	v_cvt_pk_bf16_f32 v19, v10, v11
	v_mov_b32_e32 v0, v160
	v_lshl_add_u64 v[6:7], v[0:1], 1, v[4:5]
	global_store_dwordx4 v[6:7], v[16:19], off
	s_mov_b64 s[40:41], 0
.LBB0_1027:
	v_ashrrev_i32_e32 v3, 31, v2
	v_readlane_b32 s34, v251, 39
	v_lshlrev_b64 v[6:7], 10, v[2:3]
	v_readlane_b32 s35, v251, 40
	s_andn2_b64 vcc, exec, s[40:41]
	s_nop 0
	v_lshl_add_u64 v[6:7], s[34:35], 0, v[6:7]
	s_cbranch_vccnz .LBB0_1029
	v_mov_b32_e32 v16, v161
	v_mov_b32_e32 v17, v161
	v_cvt_pk_fp8_f32 v16, v12, v13
	v_cvt_pk_fp8_f32 v17, v14, v15
	v_cvt_pk_fp8_f32 v16, v8, v9 op_sel:[0,0,1]
	v_cvt_pk_fp8_f32 v17, v10, v11 op_sel:[0,0,1]
	v_lshl_add_u64 v[8:9], v[6:7], 0, v[160:161]
	v_add_co_u32_e32 v8, vcc, 0xfffff000, v8
	s_nop 1
	v_addc_co_u32_e32 v9, vcc, -1, v9, vcc
	v_add_u32_e32 v8, 0xfffff600, v8
	v_subrev_u32_e32 v8, s100, v8
	v_lshrrev_b32_e32 v9, 3, v8
	v_bfi_b32 v9, s101, v8, v9
	v_bfe_u32 v8, v8, 7, 3
	v_lshl_add_u32 v9, v8, 21, v9
	global_store_dwordx2 v9, v[16:17], s[98:99]

; __device__ __forceinline__ unsigned pk2(float lo, float hi) { return f2bf(lo) | (f2bf(hi) << 16); }
;     __device__ __forceinline__ void operator()(const f32x4 (&acc)[2][2][4][2], const pg8::Unit& u, int wr, int wc, int fr, int fq) const {
;     ...
;                     if constexpr (MODE == 0 || MODE == 1) { v0 = v0 * scale; v1 = v1 * scale; }
;                     if constexpr (MODE == 6) { float* p = of + row * IDXW + col; *(f32x4*)p = v0; *(f32x4*)(p + 4) = v1; }
;                     else if constexpr (MODE == 0) {
;                         if (u.pn >= COL_BV / 256) {
;                             const float x8[8] = {v0[0], v0[1], v0[2], v0[3], v1[0], v1[1], v1[2], v1[3]};
;                             *(u32x2*)((unsigned char*)aux + row * 1024 + (col - COL_BV)) = to_fp8x8(x8);
;                         } else { u32x4 w; w.x = pk2(v0[0], v0[1]); w.y = pk2(v0[2], v0[3]); w.z = pk2(v1[0], v1[1]); w.w = pk2(v1[2], v1[3]);
;                             *(u32x4*)(ob + row * QKVW + col) = w; }
.LBB0_1031:
	s_andn2_b64 vcc, exec, s[34:35]
	s_cbranch_vccnz .LBB0_1033
	v_mov_b32_e32 v4, v161
	v_mov_b32_e32 v5, v161
	v_cvt_pk_fp8_f32 v4, v12, v13
	v_cvt_pk_fp8_f32 v5, v14, v15
	v_lshl_add_u64 v[6:7], v[6:7], 0, v[160:161]
	v_add_co_u32_e32 v6, vcc, 0xfffff000, v6
	v_cvt_pk_fp8_f32 v4, v8, v9 op_sel:[0,0,1]
	v_cvt_pk_fp8_f32 v5, v10, v11 op_sel:[0,0,1]
	v_addc_co_u32_e32 v7, vcc, -1, v7, vcc
	v_add_u32_e32 v6, 0xfffff680, v6
	v_subrev_u32_e32 v6, s100, v6
	v_lshrrev_b32_e32 v7, 3, v6
	v_bfi_b32 v7, s101, v6, v7
	v_bfe_u32 v6, v6, 7, 3
	v_lshl_add_u32 v7, v6, 21, v7
	global_store_dwordx2 v7, v[4:5], s[98:99]

; __device__ __forceinline__ unsigned pk2(float lo, float hi) { return f2bf(lo) | (f2bf(hi) << 16); }
;     __device__ __forceinline__ void operator()(const f32x4 (&acc)[2][2][4][2], const pg8::Unit& u, int wr, int wc, int fr, int fq) const {
;     ...
;                     if constexpr (MODE == 0 || MODE == 1) { v0 = v0 * scale; v1 = v1 * scale; }
;                     if constexpr (MODE == 6) { float* p = of + row * IDXW + col; *(f32x4*)p = v0; *(f32x4*)(p + 4) = v1; }
;                     else if constexpr (MODE == 0) {
;                         if (u.pn >= COL_BV / 256) {
;                             const float x8[8] = {v0[0], v0[1], v0[2], v0[3], v1[0], v1[1], v1[2], v1[3]};
;                             *(u32x2*)((unsigned char*)aux + row * 1024 + (col - COL_BV)) = to_fp8x8(x8);
;                         } else { u32x4 w; w.x = pk2(v0[0], v0[1]); w.y = pk2(v0[2], v0[3]); w.z = pk2(v1[0], v1[1]); w.w = pk2(v1[2], v1[3]);
;                             *(u32x4*)(ob + row * QKVW + col) = w; }
.LBB0_1035:
	v_ashrrev_i32_e32 v7, 31, v6
	v_readlane_b32 s34, v251, 39
	v_lshlrev_b64 v[6:7], 10, v[6:7]
	v_readlane_b32 s35, v251, 40
	s_andn2_b64 vcc, exec, s[44:45]
	s_nop 0
	v_lshl_add_u64 v[6:7], s[34:35], 0, v[6:7]
	s_cbranch_vccnz .LBB0_1037
	v_mov_b32_e32 v16, v161
	v_mov_b32_e32 v17, v161
	v_cvt_pk_fp8_f32 v16, v12, v13
	v_cvt_pk_fp8_f32 v17, v14, v15
	v_cvt_pk_fp8_f32 v16, v8, v9 op_sel:[0,0,1]
	v_cvt_pk_fp8_f32 v17, v10, v11 op_sel:[0,0,1]
	v_lshl_add_u64 v[8:9], v[6:7], 0, v[160:161]
	v_add_co_u32_e32 v8, vcc, 0xfffff000, v8
	s_nop 1
	v_addc_co_u32_e32 v9, vcc, -1, v9, vcc
	v_add_u32_e32 v8, 0xfffff600, v8
	v_subrev_u32_e32 v8, s100, v8
	v_lshrrev_b32_e32 v9, 3, v8
	v_bfi_b32 v9, s101, v8, v9
	v_bfe_u32 v8, v8, 7, 3
	v_lshl_add_u32 v9, v8, 21, v9
	global_store_dwordx2 v9, v[16:17], s[98:99]

; __device__ __forceinline__ unsigned pk2(float lo, float hi) { return f2bf(lo) | (f2bf(hi) << 16); }
;     __device__ __forceinline__ void operator()(const f32x4 (&acc)[2][2][4][2], const pg8::Unit& u, int wr, int wc, int fr, int fq) const {
;     ...
;                     if constexpr (MODE == 0 || MODE == 1) { v0 = v0 * scale; v1 = v1 * scale; }
;                     if constexpr (MODE == 6) { float* p = of + row * IDXW + col; *(f32x4*)p = v0; *(f32x4*)(p + 4) = v1; }
;                     else if constexpr (MODE == 0) {
;                         if (u.pn >= COL_BV / 256) {
;                             const float x8[8] = {v0[0], v0[1], v0[2], v0[3], v1[0], v1[1], v1[2], v1[3]};
;                             *(u32x2*)((unsigned char*)aux + row * 1024 + (col - COL_BV)) = to_fp8x8(x8);
;                         } else { u32x4 w; w.x = pk2(v0[0], v0[1]); w.y = pk2(v0[2], v0[3]); w.z = pk2(v1[0], v1[1]); w.w = pk2(v1[2], v1[3]);
;                             *(u32x4*)(ob + row * QKVW + col) = w; }
.LBB0_1083:
	v_ashrrev_i32_e32 v5, 31, v4
	v_readlane_b32 s34, v251, 39
	v_lshlrev_b64 v[4:5], 10, v[4:5]
	v_readlane_b32 s35, v251, 40
	s_andn2_b64 vcc, exec, s[44:45]
	s_nop 0
	v_lshl_add_u64 v[4:5], s[34:35], 0, v[4:5]
	s_cbranch_vccnz .LBB0_1085
	v_mov_b32_e32 v14, v161
	v_mov_b32_e32 v15, v161
	v_cvt_pk_fp8_f32 v14, v10, v11
	v_cvt_pk_fp8_f32 v15, v12, v13
	v_cvt_pk_fp8_f32 v14, v6, v7 op_sel:[0,0,1]
	v_cvt_pk_fp8_f32 v15, v8, v9 op_sel:[0,0,1]
	v_lshl_add_u64 v[6:7], v[4:5], 0, v[160:161]
	v_add_co_u32_e32 v6, vcc, 0xfffff000, v6
	s_nop 1
	v_addc_co_u32_e32 v7, vcc, -1, v7, vcc
	v_add_u32_e32 v6, 0xfffff600, v6
	v_subrev_u32_e32 v6, s100, v6
	v_lshrrev_b32_e32 v7, 3, v6
	v_bfi_b32 v7, s101, v6, v7
	v_bfe_u32 v6, v6, 7, 3
	v_lshl_add_u32 v7, v6, 21, v7
	global_store_dwordx2 v7, v[14:15], s[98:99]

; __device__ __forceinline__ unsigned pk2(float lo, float hi) { return f2bf(lo) | (f2bf(hi) << 16); }
;     __device__ __forceinline__ void operator()(const f32x4 (&acc)[2][2][4][2], const pg8::Unit& u, int wr, int wc, int fr, int fq) const {
;     ...
;                     if constexpr (MODE == 0 || MODE == 1) { v0 = v0 * scale; v1 = v1 * scale; }
;                     if constexpr (MODE == 6) { float* p = of + row * IDXW + col; *(f32x4*)p = v0; *(f32x4*)(p + 4) = v1; }
;                     else if constexpr (MODE == 0) {
;                         if (u.pn >= COL_BV / 256) {
;                             const float x8[8] = {v0[0], v0[1], v0[2], v0[3], v1[0], v1[1], v1[2], v1[3]};
;                             *(u32x2*)((unsigned char*)aux + row * 1024 + (col - COL_BV)) = to_fp8x8(x8);
;                         } else { u32x4 w; w.x = pk2(v0[0], v0[1]); w.y = pk2(v0[2], v0[3]); w.z = pk2(v1[0], v1[1]); w.w = pk2(v1[2], v1[3]);
;                             *(u32x4*)(ob + row * QKVW + col) = w; }
.LBB0_1089:
	v_mov_b32_e32 v0, v161
	v_mov_b32_e32 v1, v161
	v_cvt_pk_fp8_f32 v0, v10, v11
	v_cvt_pk_fp8_f32 v1, v12, v13
	v_lshl_add_u64 v[2:3], v[4:5], 0, v[160:161]
	v_add_co_u32_e32 v2, vcc, 0xfffff000, v2
	v_cvt_pk_fp8_f32 v0, v6, v7 op_sel:[0,0,1]
	v_cvt_pk_fp8_f32 v1, v8, v9 op_sel:[0,0,1]
	v_addc_co_u32_e32 v3, vcc, -1, v3, vcc
	v_add_u32_e32 v2, 0xfffff680, v2
	v_subrev_u32_e32 v2, s100, v2
	v_lshrrev_b32_e32 v3, 3, v2
	v_bfi_b32 v3, s101, v2, v3
	v_bfe_u32 v2, v2, 7, 3
	v_lshl_add_u32 v3, v2, 21, v3
	global_store_dwordx2 v3, v[0:1], s[98:99]
	s_andn2_b64 vcc, exec, s[38:39]
	s_mov_b64 s[34:35], -1
	s_cbranch_vccnz .LBB0_1018
